# attention: staging barrier moved down to the first K-tile read (K/V prefetch issue and q-tile 0 prep run before it)
# speedup vs baseline: 1.0051x; 1.0014x over previous
.LBB0_348:
	ds_read_b128 v[24:27], v242 offset:16
	ds_read_b128 v[28:31], v242 offset:144
	s_bfe_u32 s88, s33, 0x40002
	s_lshl_b32 s68, s88, 7
	v_add_u32_e32 v0, s68, v186
	v_max_i32_e32 v0, 0, v0
	v_lshlrev_b32_e32 v96, 7, v0
	v_lshl_add_u64 v[48:49], v[142:143], 0, v[96:97]
	v_lshl_add_u64 v[98:99], v[144:145], 0, v[96:97]
	s_add_i32 s58, s68, 0xffffff80
	v_add_u32_e32 v230, s58, v250
	v_lshl_add_u32 v230, v230, 7, v248
	v_max_i32_e32 v231, v248, v230
	global_load_dwordx4 v[116:119], v231, s[82:83]
	global_load_dwordx4 v[154:157], v231, s[92:93]
	v_add_u32_e32 v230, 0x400, v230
	v_max_i32_e32 v231, v248, v230
	global_load_dwordx4 v[44:47], v231, s[82:83]
	global_load_dwordx4 v[68:71], v231, s[92:93]
	v_add_u32_e32 v230, 0x400, v230
	v_max_i32_e32 v231, v248, v230
	global_load_dwordx4 v[158:161], v231, s[82:83]
	global_load_dwordx4 v[162:165], v231, s[92:93]
	v_add_u32_e32 v230, 0x400, v230
	v_max_i32_e32 v231, v248, v230
	global_load_dwordx4 v[40:43], v231, s[82:83]
	global_load_dwordx4 v[48:51], v231, s[92:93]
	ds_read_b128 v[72:75], v242
	ds_read_b128 v[16:19], v242 offset:48
	ds_read_b128 v[32:35], v242 offset:32
	ds_read_b128 v[20:23], v242 offset:176
	ds_read_b128 v[36:39], v242 offset:160
	ds_read_b128 v[76:79], v242 offset:128
	s_mov_b32 s0, s97
	s_and_b32 s97, s90, 12
	s_and_b32 s89, s96, 0xfffff800
	v_readlane_b32 s55, v255, 14
	s_waitcnt vmcnt(12)
	v_and_b32_e32 v224, 63, v251
	v_lshrrev_b32_e32 v225, 3, v224
	s_movk_i32 s58, 0x90
	v_mul_u32_u24_e32 v226, 0x1200, v254
	v_add_u32_e32 v226, 0x12000, v226
	v_and_b32_e32 v227, 7, v224
	v_lshlrev_b32_e32 v227, 4, v227
	v_mad_u32_u24 v227, v225, s58, v227
	v_add_u32_e32 v227, v227, v226
	v_lshrrev_b32_e32 v225, 1, v224
	v_and_b32_e32 v224, 1, v224
	v_lshlrev_b32_e32 v224, 5, v224
	v_mad_u32_u24 v224, v225, s58, v224
	v_add_u32_e32 v224, v224, v226
	ds_write_b128 v227, v[80:83]
	ds_write_b128 v227, v[84:87] offset:1152
	ds_write_b128 v227, v[88:91] offset:2304
	ds_write_b128 v227, v[92:95] offset:3456
	ds_read_b128 v[80:83], v224
	ds_read_b128 v[84:87], v224 offset:16
	ds_read_b128 v[92:95], v224 offset:64
	ds_read_b128 v[88:91], v224 offset:80
	s_waitcnt lgkmcnt(0)
	v_and_b32_e32 v64, 0xffff0000, v84
	v_lshlrev_b32_e32 v65, 16, v84
	v_and_b32_e32 v60, 0xffff0000, v85
	v_lshlrev_b32_e32 v61, 16, v85
	s_add_i32 s97, s97, s55
	v_or_b32_e32 v8, s89, v185
	v_and_b32_e32 v66, 0xffff0000, v88
	v_lshlrev_b32_e32 v67, 16, v88
	v_and_b32_e32 v62, 0xffff0000, v89
	v_lshlrev_b32_e32 v63, 16, v89
	v_pk_mul_f32 v[0:1], v[64:65], v[64:65]
	v_pk_mul_f32 v[2:3], v[60:61], v[60:61]
	v_or_b32_e32 v8, s68, v8
	s_lshl_b32 s94, s97, 7
	v_and_b32_e32 v56, 0xffff0000, v86
	v_lshlrev_b32_e32 v57, 16, v86
	v_and_b32_e32 v52, 0xffff0000, v87
	v_lshlrev_b32_e32 v53, 16, v87
	v_pk_fma_f32 v[214:215], v[66:67], v[66:67], v[0:1]
	v_pk_fma_f32 v[216:217], v[62:63], v[62:63], v[2:3]
	v_or_b32_e32 v2, 32, v8
	v_and_b32_e32 v58, 0xffff0000, v90
	v_lshlrev_b32_e32 v59, 16, v90
	v_and_b32_e32 v54, 0xffff0000, v91
	v_lshlrev_b32_e32 v55, 16, v91
	v_pk_mul_f32 v[4:5], v[56:57], v[56:57]
	v_pk_mul_f32 v[6:7], v[52:53], v[52:53]
	v_pk_fma_f32 v[218:219], v[58:59], v[58:59], v[4:5]
	v_pk_fma_f32 v[220:221], v[54:55], v[54:55], v[6:7]
	v_readlane_b32 s78, v255, 6
	v_readlane_b32 s79, v255, 7
	s_or_b32 s58, s89, s68
	s_or_b32 s58, s58, s91
	v_and_b32_e32 v231, 7, v250
	v_add_u32_e32 v231, s58, v231
	v_add_u32_e32 v230, s94, v248
	v_mad_u32_u24 v230, v231, s65, v230
	s_nop 0
	global_load_dwordx4 v[0:3], v230, s[78:79]
	v_add_u32_e32 v230, 0x6000, v230
	global_load_dwordx4 v[4:7], v230, s[78:79]
	v_add_u32_e32 v230, 0x6000, v230
	global_load_dwordx4 v[8:11], v230, s[78:79]
	v_add_u32_e32 v230, 0x6000, v230
	global_load_dwordx4 v[12:15], v230, s[78:79]
	v_add_u32_e32 v230, 0x6000, v230
	global_load_dwordx4 v[100:103], v230, s[78:79]
	v_add_u32_e32 v230, 0x6000, v230
	global_load_dwordx4 v[104:107], v230, s[78:79]
	v_add_u32_e32 v230, 0x6000, v230
	global_load_dwordx4 v[108:111], v230, s[78:79]
	v_add_u32_e32 v230, 0x6000, v230
	global_load_dwordx4 v[112:115], v230, s[78:79]
	v_lshlrev_b32_e32 v239, 16, v92
	v_lshlrev_b32_e32 v238, 16, v80
	v_and_b32_e32 v245, 0xffff0000, v92
	v_and_b32_e32 v244, 0xffff0000, v80
	v_lshlrev_b32_e32 v229, 16, v93
	v_lshlrev_b32_e32 v228, 16, v81
	v_pk_mul_f32 v[240:241], v[238:239], v[238:239]
	v_pk_mul_f32 v[246:247], v[244:245], v[244:245]
	v_pk_mul_f32 v[230:231], v[228:229], v[228:229]
	v_and_b32_e32 v235, 0xffff0000, v93
	v_and_b32_e32 v234, 0xffff0000, v81
	v_lshlrev_b32_e32 v171, 16, v94
	v_lshlrev_b32_e32 v170, 16, v82
	v_pk_mul_f32 v[236:237], v[234:235], v[234:235]
	v_and_b32_e32 v173, 0xffff0000, v94
	v_and_b32_e32 v172, 0xffff0000, v82
	v_pk_mul_f32 v[178:179], v[170:171], v[170:171]
	v_lshlrev_b32_e32 v167, 16, v95
	v_lshlrev_b32_e32 v166, 16, v83
	v_pk_mul_f32 v[180:181], v[172:173], v[172:173]
	v_and_b32_e32 v169, 0xffff0000, v95
	v_and_b32_e32 v168, 0xffff0000, v83
	v_pk_mul_f32 v[174:175], v[166:167], v[166:167]
	v_pk_mul_f32 v[176:177], v[168:169], v[168:169]
	v_readlane_b32 s76, v255, 1
	s_add_i32 s33, s33, s76
	v_readlane_b32 s77, v255, 2
	s_cmpk_gt_i32 s33, 0x3ff
	s_cselect_b64 s[76:77], -1, 0
	s_waitcnt lgkmcnt(0)
	v_mov_b32_e32 v98, v26
	s_waitcnt lgkmcnt(0)
	v_mov_b32_e32 v223, v28
	v_add_f32_e32 v26, v247, v246
	v_add_f32_e32 v28, v241, v240
	v_add_f32_e32 v26, v28, v26
	v_add_f32_e32 v28, v231, v230
	v_mov_b32_e32 v222, v24
	v_add_f32_e32 v24, v237, v236
	v_add_f32_e32 v26, v28, v26
	v_add_f32_e32 v24, v24, v26
	v_add_f32_e32 v26, v179, v178
	v_add_f32_e32 v24, v26, v24
	v_add_f32_e32 v26, v181, v180
	v_add_f32_e32 v24, v26, v24
	v_add_f32_e32 v26, v175, v174
	v_add_f32_e32 v24, v26, v24
	v_add_f32_e32 v26, v177, v176
	v_add_f32_e32 v24, v26, v24
	v_add_f32_e32 v24, v215, v24
	v_add_f32_e32 v24, v214, v24
	v_add_f32_e32 v24, v217, v24
	v_add_f32_e32 v24, v216, v24
	v_add_f32_e32 v24, v219, v24
	v_add_f32_e32 v24, v218, v24
	v_add_f32_e32 v24, v221, v24
	v_add_f32_e32 v24, v220, v24
	ds_bpermute_b32 v26, v187, v24
	s_waitcnt vmcnt(8)
	ds_write_b128 v227, v[116:119]
	ds_write_b128 v227, v[44:47] offset:1152
	ds_write_b128 v227, v[158:161] offset:2304
	ds_write_b128 v227, v[40:43] offset:3456
	v_and_b32_e32 v225, 63, v251
	v_lshrrev_b32_e32 v224, 1, v225
	v_and_b32_e32 v225, 1, v225
	v_lshlrev_b32_e32 v225, 6, v225
	v_mul_u32_u24_e32 v224, 0x90, v224
	v_add3_u32 v225, v224, v225, v226
	ds_read_b128 v[116:119], v225
	ds_read_b128 v[44:47], v225 offset:16
	ds_read_b128 v[158:161], v225 offset:32
	ds_read_b128 v[40:43], v225 offset:48
	ds_write_b128 v227, v[154:157]
	ds_write_b128 v227, v[68:71] offset:1152
	ds_write_b128 v227, v[162:165] offset:2304
	ds_write_b128 v227, v[48:51] offset:3456
	ds_read_b128 v[154:157], v225
	ds_read_b128 v[68:71], v225 offset:16
	ds_read_b128 v[162:165], v225 offset:32
	ds_read_b128 v[48:51], v225 offset:48
	s_waitcnt lgkmcnt(0)
	s_waitcnt lgkmcnt(0)
	v_mov_b32_e32 v176, v72
	s_waitcnt lgkmcnt(0)
	v_mov_b32_e32 v177, v76
	v_mov_b32_e32 v178, v116
	v_mov_b32_e32 v179, v154
	s_waitcnt lgkmcnt(0)
	v_add_f32_e32 v24, v24, v26
	v_fmamk_f32 v24, v24, 0x3c800000, v189
	v_rsq_f32_e32 v24, v24
	v_mov_b32_e32 v76, v73
	v_mov_b32_e32 v232, v74
	v_mov_b32_e32 v233, v78
	v_pk_mul_f32 v[180:181], v[24:25], v[238:239] op_sel_hi:[0,1]
	v_pk_mul_f32 v[176:177], v[176:177], v[180:181]
	v_mov_b32_e32 v174, v118
	v_pk_mul_f32 v[178:179], v[178:179], v[176:177]
	v_mov_b32_e32 v175, v156
	v_sub_f32_e32 v96, v178, v179
	v_mov_b32_e32 v178, v154
	v_mov_b32_e32 v179, v116
	v_pk_mul_f32 v[176:177], v[178:179], v[176:177]
	v_mov_b32_e32 v154, v117
	v_add_f32_e32 v153, v177, v176
	v_pk_mul_f32 v[176:177], v[24:25], v[244:245] op_sel_hi:[0,1]
	v_pk_mul_f32 v[72:73], v[76:77], v[176:177]
	v_mov_b32_e32 v116, v155
	v_pk_mul_f32 v[76:77], v[154:155], v[72:73]
	v_pk_mul_f32 v[72:73], v[116:117], v[72:73]
	v_sub_f32_e32 v154, v76, v77
	v_add_f32_e32 v116, v73, v72
	v_pk_mul_f32 v[72:73], v[24:25], v[228:229] op_sel_hi:[0,1]
	v_pk_mul_f32 v[72:73], v[232:233], v[72:73]
	v_mov_b32_e32 v78, v75
	v_pk_mul_f32 v[76:77], v[174:175], v[72:73]
	v_mov_b32_e32 v226, v44
	v_sub_f32_e32 v117, v76, v77
	v_mov_b32_e32 v76, v156
	v_mov_b32_e32 v77, v118
	v_pk_mul_f32 v[72:73], v[76:77], v[72:73]
	v_mov_b32_e32 v156, v119
	v_add_f32_e32 v76, v73, v72
	v_pk_mul_f32 v[72:73], v[24:25], v[234:235] op_sel_hi:[0,1]
	v_pk_mul_f32 v[72:73], v[78:79], v[72:73]
	v_mov_b32_e32 v118, v157
	v_pk_mul_f32 v[74:75], v[156:157], v[72:73]
	v_pk_mul_f32 v[72:73], v[118:119], v[72:73]
	v_mov_b32_e32 v227, v68
	v_add_f32_e32 v78, v73, v72
	v_pk_mul_f32 v[72:73], v[24:25], v[170:171] op_sel_hi:[0,1]
	v_pk_mul_f32 v[72:73], v[72:73], v[222:223]
	v_sub_f32_e32 v77, v74, v75
	v_pk_mul_f32 v[74:75], v[72:73], v[226:227]
	v_mov_b32_e32 v28, v25
	v_sub_f32_e32 v79, v74, v75
	v_mov_b32_e32 v74, v68
	v_mov_b32_e32 v75, v44
	v_pk_mul_f32 v[72:73], v[72:73], v[74:75]
	v_mov_b32_e32 v68, v45
	v_add_f32_e32 v74, v73, v72
	v_pk_mul_f32 v[72:73], v[24:25], v[172:173] op_sel_hi:[0,1]
	v_pk_mul_f32 v[28:29], v[72:73], v[28:29]
	v_mov_b32_e32 v44, v69
	v_pk_mul_f32 v[72:73], v[28:29], v[68:69]
	v_pk_mul_f32 v[28:29], v[28:29], v[44:45]
	v_sub_f32_e32 v25, v72, v73
	v_mov_b32_e32 v99, v30
	v_add_f32_e32 v68, v29, v28
	v_pk_mul_f32 v[28:29], v[24:25], v[166:167] op_sel_hi:[0,1]
	v_mov_b32_e32 v224, v46
	v_mov_b32_e32 v225, v70
	v_pk_mul_f32 v[28:29], v[28:29], v[98:99]
	v_mov_b32_e32 v30, v27
	v_pk_mul_f32 v[44:45], v[28:29], v[224:225]
	s_and_b64 vcc, exec, s[76:77]
	v_sub_f32_e32 v69, v44, v45
	v_mov_b32_e32 v44, v70
	v_mov_b32_e32 v45, v46
	v_pk_mul_f32 v[28:29], v[28:29], v[44:45]
	v_mov_b32_e32 v70, v47
	v_add_f32_e32 v44, v29, v28
	v_pk_mul_f32 v[28:29], v[24:25], v[168:169] op_sel_hi:[0,1]
	v_pk_mul_f32 v[26:27], v[28:29], v[30:31]
	v_mov_b32_e32 v46, v71
	v_pk_mul_f32 v[28:29], v[26:27], v[70:71]
	v_pk_mul_f32 v[26:27], v[26:27], v[46:47]
	v_sub_f32_e32 v30, v28, v29
	v_add_f32_e32 v31, v27, v26
	v_mov_b32_e32 v26, v65
	v_mov_b32_e32 v27, v67
	v_pk_mul_f32 v[26:27], v[24:25], v[26:27] op_sel_hi:[0,1]
	v_mov_b32_e32 v28, v32
	v_mov_b32_e32 v29, v36
	v_pk_mul_f32 v[26:27], v[26:27], v[28:29]
	v_mov_b32_e32 v28, v158
	v_mov_b32_e32 v29, v162
	v_pk_mul_f32 v[28:29], v[26:27], v[28:29]
	v_mov_b32_e32 v65, v66
	v_sub_f32_e32 v32, v28, v29
	v_mov_b32_e32 v28, v162
	v_mov_b32_e32 v29, v158
	v_pk_mul_f32 v[26:27], v[26:27], v[28:29]
	v_mov_b32_e32 v36, v33
	v_add_f32_e32 v45, v27, v26
	v_pk_mul_f32 v[26:27], v[24:25], v[64:65] op_sel_hi:[0,1]
	v_pk_mul_f32 v[26:27], v[26:27], v[36:37]
	v_mov_b32_e32 v162, v159
	v_mov_b32_e32 v158, v163
	v_pk_mul_f32 v[28:29], v[26:27], v[162:163]
	v_pk_mul_f32 v[26:27], v[26:27], v[158:159]
	v_sub_f32_e32 v33, v28, v29
	v_add_f32_e32 v36, v27, v26
	v_mov_b32_e32 v26, v61
	v_mov_b32_e32 v27, v63
	v_pk_mul_f32 v[26:27], v[24:25], v[26:27] op_sel_hi:[0,1]
	v_mov_b32_e32 v28, v34
	v_mov_b32_e32 v29, v38
	v_pk_mul_f32 v[26:27], v[26:27], v[28:29]
	v_mov_b32_e32 v28, v160
	v_mov_b32_e32 v29, v164
	v_pk_mul_f32 v[28:29], v[26:27], v[28:29]
	v_mov_b32_e32 v61, v62
	v_sub_f32_e32 v34, v28, v29
	v_mov_b32_e32 v28, v164
	v_mov_b32_e32 v29, v160
	v_pk_mul_f32 v[26:27], v[26:27], v[28:29]
	v_mov_b32_e32 v38, v35
	v_add_f32_e32 v37, v27, v26
	v_pk_mul_f32 v[26:27], v[24:25], v[60:61] op_sel_hi:[0,1]
	v_pk_mul_f32 v[26:27], v[26:27], v[38:39]
	v_mov_b32_e32 v164, v161
	v_mov_b32_e32 v160, v165
	v_pk_mul_f32 v[28:29], v[26:27], v[164:165]
	v_pk_mul_f32 v[26:27], v[26:27], v[160:161]
	v_sub_f32_e32 v35, v28, v29
	v_add_f32_e32 v38, v27, v26
	v_mov_b32_e32 v26, v57
	v_mov_b32_e32 v27, v59
	v_pk_mul_f32 v[26:27], v[24:25], v[26:27] op_sel_hi:[0,1]
	v_mov_b32_e32 v28, v16
	v_mov_b32_e32 v29, v20
	v_pk_mul_f32 v[26:27], v[26:27], v[28:29]
	v_mov_b32_e32 v28, v40
	v_mov_b32_e32 v29, v48
	v_pk_mul_f32 v[28:29], v[26:27], v[28:29]
	v_mov_b32_e32 v57, v58
	v_sub_f32_e32 v39, v28, v29
	v_mov_b32_e32 v28, v48
	v_mov_b32_e32 v29, v40
	v_pk_mul_f32 v[26:27], v[26:27], v[28:29]
	v_mov_b32_e32 v20, v17
	v_add_f32_e32 v28, v27, v26
	v_pk_mul_f32 v[26:27], v[24:25], v[56:57] op_sel_hi:[0,1]
	v_pk_mul_f32 v[16:17], v[26:27], v[20:21]
	v_mov_b32_e32 v48, v41
	v_mov_b32_e32 v40, v49
	v_pk_mul_f32 v[20:21], v[16:17], v[48:49]
	v_pk_mul_f32 v[16:17], v[16:17], v[40:41]
	v_sub_f32_e32 v26, v20, v21
	v_add_f32_e32 v27, v17, v16
	v_mov_b32_e32 v16, v53
	v_mov_b32_e32 v17, v55
	v_pk_mul_f32 v[16:17], v[24:25], v[16:17] op_sel_hi:[0,1]
	v_mov_b32_e32 v20, v18
	v_mov_b32_e32 v21, v22
	v_pk_mul_f32 v[16:17], v[16:17], v[20:21]
	v_mov_b32_e32 v20, v42
	v_mov_b32_e32 v21, v50
	v_pk_mul_f32 v[20:21], v[16:17], v[20:21]
	v_mov_b32_e32 v53, v54
	v_sub_f32_e32 v29, v20, v21
	v_mov_b32_e32 v20, v50
	v_mov_b32_e32 v21, v42
	v_pk_mul_f32 v[16:17], v[16:17], v[20:21]
	v_mov_b32_e32 v22, v19
	v_add_f32_e32 v20, v17, v16
	v_pk_mul_f32 v[16:17], v[24:25], v[52:53] op_sel_hi:[0,1]
	v_pk_mul_f32 v[16:17], v[16:17], v[22:23]
	v_mov_b32_e32 v50, v43
	v_mov_b32_e32 v42, v51
	v_pk_mul_f32 v[18:19], v[16:17], v[50:51]
	v_pk_mul_f32 v[16:17], v[16:17], v[42:43]
	v_sub_f32_e32 v21, v18, v19
	v_add_f32_e32 v22, v17, v16
	v_cvt_pk_bf16_f32 v16, v96, v154
	v_cvt_pk_bf16_f32 v17, v117, v77
	v_cvt_pk_bf16_f32 v18, v79, v25
	v_cvt_pk_bf16_f32 v19, v69, v30
	s_barrier
	ds_write_b128 v190, v[16:19]
	v_cvt_pk_bf16_f32 v16, v32, v33
	v_cvt_pk_bf16_f32 v17, v34, v35
	v_cvt_pk_bf16_f32 v18, v39, v26
	v_cvt_pk_bf16_f32 v19, v29, v21
	ds_write_b128 v190, v[16:19] offset:16
	v_cvt_pk_bf16_f32 v16, v153, v116
	v_cvt_pk_bf16_f32 v17, v76, v78
	v_cvt_pk_bf16_f32 v18, v74, v68
	v_cvt_pk_bf16_f32 v19, v44, v31
	ds_write_b128 v190, v[16:19] offset:64
	v_cvt_pk_bf16_f32 v16, v45, v36
	v_cvt_pk_bf16_f32 v17, v37, v38
	v_cvt_pk_bf16_f32 v18, v28, v27
	v_cvt_pk_bf16_f32 v19, v20, v22
	ds_write_b128 v190, v[16:19] offset:80
	v_and_b32_e32 v20, 63, v251
	v_lshrrev_b32_e32 v21, 3, v20
	v_mul_u32_u24_e32 v21, 0x90, v21
	v_and_b32_e32 v22, 7, v20
	v_lshl_add_u32 v21, v22, 4, v21
	v_mul_u32_u24_e32 v22, 0x1200, v254
	v_add_u32_e32 v22, 0x12000, v22
	v_add_u32_e32 v21, v21, v22
	v_lshrrev_b32_e32 v23, 2, v20
	v_mul_u32_u24_e32 v23, 0x120, v23
	v_and_b32_e32 v20, 3, v20
	v_lshl_add_u32 v23, v20, 3, v23
	v_add_u32_e32 v23, v23, v22
	ds_write_b128 v21, v[122:125]
	ds_write_b128 v21, v[128:131] offset:1152
	ds_write_b128 v21, v[132:135] offset:2304
	ds_write_b128 v21, v[136:139] offset:3456
	ds_read_b64 v[122:123], v23
	ds_read_b64 v[124:125], v23 offset:32
	ds_read_b64 v[128:129], v23 offset:64
	ds_read_b64 v[130:131], v23 offset:96
	ds_read_b64 v[132:133], v23 offset:144
	ds_read_b64 v[136:137], v23 offset:176
	ds_read_b64 v[138:139], v23 offset:208
	ds_read_b64 v[140:141], v23 offset:240
	s_waitcnt lgkmcnt(0)
	v_and_b32_e32 v16, 0xffff, v122
	v_lshrrev_b32_e32 v17, 16, v122
	v_lshl_or_b32 v16, v132, 16, v16
	v_and_or_b32 v17, v132, s54, v17
	v_add_u32_e32 v18, 0x9000, v191
	ds_write2_b32 v18, v16, v17 offset1:130
	v_and_b32_e32 v16, 0xffff, v123
	v_lshrrev_b32_e32 v17, 16, v123
	v_lshl_or_b32 v16, v133, 16, v16
	v_and_or_b32 v17, v133, s54, v17
	v_add_u32_e32 v18, 0x9400, v191
	ds_write2_b32 v18, v16, v17 offset0:4 offset1:134
	v_and_b32_e32 v16, 0xffff, v124
	v_lshrrev_b32_e32 v17, 16, v124
	v_lshl_or_b32 v16, v136, 16, v16
	v_and_or_b32 v17, v136, s54, v17
	v_add_u32_e32 v18, 0xb000, v191
	ds_write2_b32 v18, v16, v17 offset0:32 offset1:162
	v_and_b32_e32 v16, 0xffff, v125
	v_lshrrev_b32_e32 v17, 16, v125
	v_lshl_or_b32 v16, v137, 16, v16
	v_and_or_b32 v17, v137, s54, v17
	v_add_u32_e32 v18, 0xb400, v191
	ds_write2_b32 v18, v16, v17 offset0:36 offset1:166
	v_and_b32_e32 v16, 0xffff, v128
	v_lshrrev_b32_e32 v17, 16, v128
	v_lshl_or_b32 v16, v138, 16, v16
	v_and_or_b32 v17, v138, s54, v17
	v_add_u32_e32 v18, 0xd000, v191
	ds_write2_b32 v18, v16, v17 offset0:64 offset1:194
	v_and_b32_e32 v16, 0xffff, v129
	v_lshrrev_b32_e32 v17, 16, v129
	v_lshl_or_b32 v16, v139, 16, v16
	v_and_or_b32 v17, v139, s54, v17
	v_add_u32_e32 v18, 0xd400, v191
	ds_write2_b32 v18, v16, v17 offset0:68 offset1:198
	v_and_b32_e32 v16, 0xffff, v130
	v_lshrrev_b32_e32 v17, 16, v130
	v_lshl_or_b32 v16, v140, 16, v16
	v_and_or_b32 v17, v140, s54, v17
	v_add_u32_e32 v18, 0xf000, v191
	ds_write2_b32 v18, v16, v17 offset0:96 offset1:226
	v_and_b32_e32 v16, 0xffff, v131
	v_lshrrev_b32_e32 v17, 16, v131
	v_lshl_or_b32 v16, v141, 16, v16
	v_and_or_b32 v17, v141, s54, v17
	v_add_u32_e32 v18, 0xf400, v191
	ds_write2_b32 v18, v16, v17 offset0:100 offset1:230
	s_waitcnt vmcnt(0)
	v_and_b32_e32 v16, 63, v251
	v_lshrrev_b32_e32 v17, 3, v16
	v_mul_u32_u24_e32 v17, 0x90, v17
	v_and_b32_e32 v18, 7, v16
	v_lshl_add_u32 v17, v18, 4, v17
	v_mul_u32_u24_e32 v18, 0x1200, v254
	v_add_u32_e32 v18, 0x12000, v18
	v_add_u32_e32 v17, v17, v18
	v_and_b32_e32 v19, 31, v16
	v_mul_u32_u24_e32 v19, 0x90, v19
	v_lshrrev_b32_e32 v16, 5, v16
	v_lshl_add_u32 v19, v16, 4, v19
	v_add_u32_e32 v19, v19, v18
	ds_write_b128 v17, v[0:3]
	ds_write_b128 v17, v[4:7] offset:1152
	ds_write_b128 v17, v[8:11] offset:2304
	ds_write_b128 v17, v[12:15] offset:3456
	ds_read_b128 v[0:3], v19
	ds_read_b128 v[8:11], v19 offset:32
	ds_read_b128 v[4:7], v19 offset:64
	ds_read_b128 v[12:15], v19 offset:96
	ds_write_b128 v17, v[100:103]
	ds_write_b128 v17, v[104:107] offset:1152
	ds_write_b128 v17, v[108:111] offset:2304
	ds_write_b128 v17, v[112:115] offset:3456
	ds_read_b128 v[100:103], v19
	ds_read_b128 v[108:111], v19 offset:32
	ds_read_b128 v[104:107], v19 offset:64
	ds_read_b128 v[112:115], v19 offset:96
	s_waitcnt lgkmcnt(0)
	s_cbranch_vccnz .LBB0_354
	s_add_i32 s64, s1, s96
	s_and_b32 s64, s64, 0x780
	s_addk_i32 s64, 0xff80
	v_mov_b32_e32 v96, v97
	v_add_u32_e32 v16, s64, v182
	v_mov_b32_e32 v98, v97
	v_mov_b32_e32 v99, v97
	v_mov_b64_e32 v[80:81], v[96:97]
	v_mov_b64_e32 v[84:85], v[96:97]
	v_mov_b64_e32 v[92:93], v[96:97]
	v_mov_b64_e32 v[88:89], v[96:97]
	s_ashr_i32 s55, s33, 6
	s_and_b32 s69, s33, 3
	v_cmp_lt_i32_e32 vcc, -1, v16
	v_mov_b64_e32 v[82:83], v[98:99]
	v_mov_b64_e32 v[86:87], v[98:99]
	v_mov_b64_e32 v[94:95], v[98:99]
	v_mov_b64_e32 v[90:91], v[98:99]
	s_and_saveexec_b64 s[78:79], vcc
	s_cbranch_execz .LBB0_351
	v_readlane_b32 vcc_lo, v255, 6
	v_readlane_b32 vcc_hi, v255, 7
	v_add_u32_e32 v18, s64, v250
	v_lshl_add_u32 v18, s55, 11, v18
	s_lshl_b32 s94, s69, 7
	v_mov_b64_e32 v[16:17], vcc
	v_mad_i64_i32 v[16:17], vcc, v18, s65, v[16:17]
	v_lshl_add_u64 v[16:17], v[16:17], 0, s[94:95]
	v_mov_b32_e32 v153, v97
	v_lshl_add_u64 v[16:17], v[16:17], 0, v[248:249]
	s_movk_i32 s94, 0x6000
	global_load_dwordx4 v[80:83], v[16:17], off offset:2048
	v_lshl_add_u64 v[16:17], v[16:17], 0, s[94:95]
	global_load_dwordx4 v[84:87], v[16:17], off offset:2048
	v_lshl_add_u64 v[16:17], v[16:17], 0, s[94:95]
	global_load_dwordx4 v[88:91], v[16:17], off offset:2048
	v_lshl_add_u64 v[16:17], v[16:17], 0, s[94:95]
	global_load_dwordx4 v[92:95], v[16:17], off offset:2048

.Lattn_prio_skip:
	ds_read_b128 v[20:23], v243 offset:144
	ds_read_b128 v[16:19], v243 offset:16
	v_or_b32_e32 v153, s68, v184
	v_or_b32_e32 v98, s91, v153
	v_lshlrev_b32_e32 v96, 5, v98
	v_or_b32_e32 v24, v96, v126
	v_lshlrev_b32_e32 v54, 2, v24
	ds_read_b128 v[42:45], v243 offset:128
	ds_read_b128 v[24:27], v252 offset:4096
	ds_read_b128 v[28:31], v252 offset:22144
	ds_read_b128 v[46:49], v243
	ds_read_b128 v[50:53], v252
	s_nop 0
	ds_read_b128 v[54:57], v252 offset:16384
	s_lshl_b32 s55, s97, 2
	v_lshlrev_b32_e32 v34, 16, v15
	v_and_b32_e32 v32, 0xffff0000, v15
	v_lshlrev_b32_e32 v39, 16, v9
	v_and_b32_e32 v15, 0xffff0000, v9
	v_lshlrev_b32_e32 v41, 16, v8
	v_lshlrev_b32_e32 v40, 16, v12
	v_and_b32_e32 v9, 0xffff0000, v8
	v_and_b32_e32 v8, 0xffff0000, v12
	v_lshlrev_b32_e32 v12, 16, v7
	v_and_b32_e32 v58, 0xffff0000, v7
	v_lshlrev_b32_e32 v7, 16, v1
	v_and_b32_e32 v63, 0xffff0000, v1
	v_lshlrev_b32_e32 v65, 16, v0
	v_lshlrev_b32_e32 v64, 16, v4
	v_and_b32_e32 v1, 0xffff0000, v0
	v_and_b32_e32 v0, 0xffff0000, v4
	v_lshlrev_b32_e32 v35, 16, v11
	v_and_b32_e32 v33, 0xffff0000, v11
	v_lshlrev_b32_e32 v36, 16, v14
	v_lshlrev_b32_e32 v37, 16, v10
	v_and_b32_e32 v11, 0xffff0000, v10
	v_and_b32_e32 v10, 0xffff0000, v14
	v_lshlrev_b32_e32 v38, 16, v13
	v_and_b32_e32 v14, 0xffff0000, v13
	v_lshlrev_b32_e32 v13, 16, v3
	v_and_b32_e32 v59, 0xffff0000, v3
	v_lshlrev_b32_e32 v61, 16, v2
	v_lshlrev_b32_e32 v60, 16, v6
	v_and_b32_e32 v3, 0xffff0000, v2
	v_and_b32_e32 v2, 0xffff0000, v6
	v_lshlrev_b32_e32 v6, 16, v5
	v_mov_b32_e32 v99, s55
	v_pk_mul_f32 v[156:157], v[64:65], v[64:65]
	v_pk_mul_f32 v[158:159], v[0:1], v[0:1]
	v_and_b32_e32 v62, 0xffff0000, v5
	v_pk_mul_f32 v[118:119], v[6:7], v[6:7]
	v_mov_b32_e32 v214, v253
	v_add_f32_e32 v99, v157, v159
	v_pk_mul_f32 v[154:155], v[62:63], v[62:63]
	v_add_f32_e32 v99, v119, v99
	v_pk_mul_f32 v[78:79], v[60:61], v[60:61]
	v_add_f32_e32 v99, v155, v99
	v_pk_mul_f32 v[116:117], v[2:3], v[2:3]
	v_add_f32_e32 v79, v79, v99
	v_pk_mul_f32 v[74:75], v[12:13], v[12:13]
	v_add_f32_e32 v79, v117, v79
	v_pk_mul_f32 v[76:77], v[58:59], v[58:59]
	v_add_f32_e32 v75, v75, v79
	v_pk_mul_f32 v[70:71], v[40:41], v[40:41]
	v_add_f32_e32 v75, v77, v75
	v_pk_mul_f32 v[72:73], v[8:9], v[8:9]
	v_add_f32_e32 v71, v71, v75
	v_add_f32_e32 v71, v73, v71
	v_fmac_f32_e32 v71, v39, v39
	v_fmac_f32_e32 v71, v15, v15
	v_fmac_f32_e32 v71, v37, v37
	v_fmac_f32_e32 v71, v11, v11
	v_fmac_f32_e32 v71, v35, v35
	v_fmac_f32_e32 v71, v33, v33
	v_mov_b32_e32 v68, v14
	v_mov_b32_e32 v69, v38
	v_pk_mul_f32 v[68:69], v[68:69], v[68:69]
	v_mov_b32_e32 v66, v10
	v_mov_b32_e32 v67, v36
	v_pk_mul_f32 v[66:67], v[66:67], v[66:67]
	v_mov_b32_e32 v4, v32
	v_mov_b32_e32 v5, v34
	v_pk_mul_f32 v[4:5], v[4:5], v[4:5]
	s_waitcnt lgkmcnt(0)
	v_mov_b32_e32 v162, v20
	s_waitcnt lgkmcnt(0)
	v_mov_b32_e32 v163, v16
	v_add_f32_e32 v16, v156, v71
	v_add_f32_e32 v16, v158, v16
	v_add_f32_e32 v16, v118, v16
	v_add_f32_e32 v16, v154, v16
	v_add_f32_e32 v16, v78, v16
	v_add_f32_e32 v16, v116, v16
	v_add_f32_e32 v16, v74, v16
	v_add_f32_e32 v16, v76, v16
	v_add_f32_e32 v16, v70, v16
	v_add_f32_e32 v16, v72, v16
	v_add_f32_e32 v16, v69, v16
	v_add_f32_e32 v16, v68, v16
	v_add_f32_e32 v16, v67, v16
	v_add_f32_e32 v16, v66, v16
	v_add_f32_e32 v5, v5, v16
	v_add_f32_e32 v16, v4, v5
	v_mov_b32_e32 v161, v18
	ds_bpermute_b32 v18, v188, v16
	s_waitcnt lgkmcnt(0)
	v_mov_b32_e32 v66, v42
	s_waitcnt lgkmcnt(0)
	v_mov_b32_e32 v67, v46
	v_mov_b32_e32 v46, v43
	v_mov_b32_e32 v68, v50
	s_waitcnt lgkmcnt(0)
	v_add_f32_e32 v16, v16, v18
	v_fmamk_f32 v16, v16, 0x3c800000, v189
	v_rsq_f32_e32 v16, v16
	v_mov_b32_e32 v69, v54
	v_mov_b32_e32 v164, v44
	v_mov_b32_e32 v165, v48
	v_mul_f32_e32 v70, 0x3e38aa3b, v16
	v_pk_mul_f32 v[64:65], v[70:71], v[64:65] op_sel_hi:[0,1]
	v_pk_mul_f32 v[0:1], v[70:71], v[0:1] op_sel_hi:[0,1]
	v_pk_mul_f32 v[64:65], v[66:67], v[64:65]
	v_mov_b32_e32 v66, v54
	v_mov_b32_e32 v67, v50
	v_pk_mul_f32 v[0:1], v[46:47], v[0:1]
	v_mov_b32_e32 v50, v55
	v_mov_b32_e32 v54, v51
	v_pk_mul_f32 v[42:43], v[50:51], v[0:1]
	v_pk_mul_f32 v[0:1], v[54:55], v[0:1]
	v_sub_f32_e32 v42, v43, v42
	v_add_f32_e32 v43, v0, v1
	v_pk_mul_f32 v[0:1], v[70:71], v[6:7] op_sel_hi:[0,1]
	v_mov_b32_e32 v4, v52
	v_mov_b32_e32 v5, v56
	v_pk_mul_f32 v[0:1], v[0:1], v[164:165]
	v_mov_b32_e32 v6, v56
	v_mov_b32_e32 v7, v52
	v_pk_mul_f32 v[6:7], v[0:1], v[6:7]
	v_pk_mul_f32 v[0:1], v[0:1], v[4:5]
	v_sub_f32_e32 v6, v7, v6
	v_add_f32_e32 v7, v0, v1
	v_pk_mul_f32 v[0:1], v[70:71], v[62:63] op_sel_hi:[0,1]
	v_mov_b32_e32 v48, v45
	v_pk_mul_f32 v[0:1], v[0:1], v[48:49]
	v_mov_b32_e32 v52, v57
	v_mov_b32_e32 v56, v53
	v_pk_mul_f32 v[4:5], v[0:1], v[52:53]
	v_pk_mul_f32 v[0:1], v[0:1], v[56:57]
	v_mov_b32_e32 v168, v24
	v_add_f32_e32 v45, v0, v1
	v_pk_mul_f32 v[0:1], v[70:71], v[60:61] op_sel_hi:[0,1]
	v_mov_b32_e32 v169, v28
	v_sub_f32_e32 v44, v5, v4
	v_pk_mul_f32 v[0:1], v[0:1], v[162:163]
	v_mov_b32_e32 v4, v28
	v_mov_b32_e32 v5, v24
	v_pk_mul_f32 v[4:5], v[0:1], v[4:5]
	v_pk_mul_f32 v[0:1], v[0:1], v[168:169]
	v_sub_f32_e32 v4, v5, v4
	v_add_f32_e32 v5, v0, v1
	v_pk_mul_f32 v[0:1], v[70:71], v[2:3] op_sel_hi:[0,1]
	v_mov_b32_e32 v16, v21
	v_pk_mul_f32 v[0:1], v[0:1], v[16:17]
	v_mov_b32_e32 v24, v29
	v_mov_b32_e32 v28, v25
	v_pk_mul_f32 v[2:3], v[0:1], v[24:25]
	v_pk_mul_f32 v[0:1], v[0:1], v[28:29]
	v_mov_b32_e32 v160, v22
	v_add_f32_e32 v17, v0, v1
	v_pk_mul_f32 v[0:1], v[70:71], v[12:13] op_sel_hi:[0,1]
	v_mov_b32_e32 v166, v26
	v_mov_b32_e32 v167, v30
	v_sub_f32_e32 v16, v3, v2
	v_pk_mul_f32 v[0:1], v[0:1], v[160:161]
	v_mov_b32_e32 v2, v30
	v_mov_b32_e32 v3, v26
	v_pk_mul_f32 v[2:3], v[0:1], v[2:3]
	v_pk_mul_f32 v[0:1], v[0:1], v[166:167]
	v_mov_b32_e32 v18, v23
	v_add_f32_e32 v13, v0, v1
	v_pk_mul_f32 v[0:1], v[70:71], v[58:59] op_sel_hi:[0,1]
	v_pk_mul_f32 v[0:1], v[0:1], v[18:19]
	v_mov_b32_e32 v26, v31
	v_mov_b32_e32 v30, v27
	v_sub_f32_e32 v12, v3, v2
	v_pk_mul_f32 v[2:3], v[0:1], v[26:27]
	v_pk_mul_f32 v[0:1], v[0:1], v[30:31]
	v_pk_mul_f32 v[66:67], v[66:67], v[64:65]
	v_pk_mul_f32 v[64:65], v[68:69], v[64:65]
	v_sub_f32_e32 v2, v3, v2
	v_add_f32_e32 v0, v0, v1
	v_sub_f32_e32 v20, v67, v66
	v_add_f32_e32 v22, v64, v65
	v_cvt_pk_bf16_f32 v48, v20, v42
	v_cvt_pk_bf16_f32 v49, v6, v44
	v_cvt_pk_bf16_f32 v50, v4, v16
	v_cvt_pk_bf16_f32 v51, v12, v2
	v_cvt_pk_bf16_f32 v116, v22, v43
	v_cvt_pk_bf16_f32 v117, v7, v45
	v_cvt_pk_bf16_f32 v118, v5, v17
	v_cvt_pk_bf16_f32 v119, v13, v0
	ds_read_b128 v[0:3], v243 offset:192
	ds_read_b128 v[4:7], v243 offset:64
	v_or_b32_e32 v96, v96, v127
	v_lshlrev_b32_e32 v12, 2, v96
	ds_read_b128 v[16:19], v252 offset:26240
	ds_read_b128 v[20:23], v252 offset:8192
	ds_read_b128 v[24:27], v243 offset:208
	ds_read_b128 v[28:31], v243 offset:80
	ds_read_b128 v[42:45], v252 offset:30336
	ds_read_b128 v[52:55], v252 offset:12288
	v_pk_mul_f32 v[12:13], v[70:71], v[40:41] op_sel_hi:[0,1]
	v_pk_mul_f32 v[8:9], v[70:71], v[8:9] op_sel_hi:[0,1]
	s_lshl_b32 s69, s97, 6
	s_cmp_eq_u32 s88, 0
	s_cselect_b64 s[78:79], -1, 0
	s_cmp_lg_u32 s88, 0
	s_waitcnt lgkmcnt(0)
	v_mov_b32_e32 v40, v0
	s_waitcnt lgkmcnt(0)
	v_mov_b32_e32 v41, v4
	v_pk_mul_f32 v[12:13], v[12:13], v[40:41]
	v_mov_b32_e32 v40, v16
	v_mov_b32_e32 v41, v20
	v_pk_mul_f32 v[40:41], v[12:13], v[40:41]
	v_mov_b32_e32 v4, v1
	v_sub_f32_e32 v46, v41, v40
	v_mov_b32_e32 v40, v20
	v_mov_b32_e32 v41, v16
	v_pk_mul_f32 v[0:1], v[8:9], v[4:5]
	v_mov_b32_e32 v20, v17
	v_mov_b32_e32 v16, v21
	v_pk_mul_f32 v[4:5], v[0:1], v[20:21]
	v_pk_mul_f32 v[0:1], v[0:1], v[16:17]
	v_sub_f32_e32 v8, v5, v4
	v_add_f32_e32 v9, v0, v1
	v_pk_mul_f32 v[0:1], v[70:71], v[38:39] op_sel_hi:[0,1]
	v_mov_b32_e32 v4, v2
	v_mov_b32_e32 v5, v6
	v_pk_mul_f32 v[0:1], v[0:1], v[4:5]
	v_mov_b32_e32 v4, v18
	v_mov_b32_e32 v5, v22
	v_pk_mul_f32 v[12:13], v[12:13], v[40:41]
	v_pk_mul_f32 v[4:5], v[0:1], v[4:5]
	v_add_f32_e32 v12, v12, v13
	v_sub_f32_e32 v13, v5, v4
	v_mov_b32_e32 v4, v22
	v_mov_b32_e32 v5, v18
	v_pk_mul_f32 v[0:1], v[0:1], v[4:5]
	v_mov_b32_e32 v6, v3
	v_add_f32_e32 v4, v0, v1
	v_pk_mul_f32 v[0:1], v[70:71], v[14:15] op_sel_hi:[0,1]
	v_pk_mul_f32 v[0:1], v[0:1], v[6:7]
	v_mov_b32_e32 v22, v19
	v_mov_b32_e32 v18, v23
	v_pk_mul_f32 v[2:3], v[0:1], v[22:23]
	v_pk_mul_f32 v[0:1], v[0:1], v[18:19]
	v_sub_f32_e32 v5, v3, v2
	v_add_f32_e32 v6, v0, v1
	v_pk_mul_f32 v[0:1], v[70:71], v[36:37] op_sel_hi:[0,1]
	s_waitcnt lgkmcnt(0)
	v_mov_b32_e32 v2, v24
	s_waitcnt lgkmcnt(0)
	v_mov_b32_e32 v3, v28
	v_pk_mul_f32 v[0:1], v[0:1], v[2:3]
	v_mov_b32_e32 v2, v42
	v_mov_b32_e32 v3, v52
	v_pk_mul_f32 v[2:3], v[0:1], v[2:3]
	v_mov_b32_e32 v28, v25
	v_sub_f32_e32 v7, v3, v2
	v_mov_b32_e32 v2, v52
	v_mov_b32_e32 v3, v42
	v_pk_mul_f32 v[0:1], v[0:1], v[2:3]
	v_mov_b32_e32 v52, v43
	v_add_f32_e32 v14, v0, v1
	v_pk_mul_f32 v[0:1], v[70:71], v[10:11] op_sel_hi:[0,1]
	v_pk_mul_f32 v[0:1], v[0:1], v[28:29]
	v_mov_b32_e32 v42, v53
	v_pk_mul_f32 v[2:3], v[0:1], v[52:53]
	v_pk_mul_f32 v[0:1], v[0:1], v[42:43]
	v_sub_f32_e32 v10, v3, v2
	v_add_f32_e32 v11, v0, v1
	v_pk_mul_f32 v[0:1], v[70:71], v[34:35] op_sel_hi:[0,1]
	v_mov_b32_e32 v2, v26
	v_mov_b32_e32 v3, v30
	v_pk_mul_f32 v[0:1], v[0:1], v[2:3]
	v_mov_b32_e32 v2, v44
	v_mov_b32_e32 v3, v54
	v_pk_mul_f32 v[2:3], v[0:1], v[2:3]
	v_mov_b32_e32 v30, v27
	v_sub_f32_e32 v15, v3, v2
	v_mov_b32_e32 v2, v54
	v_mov_b32_e32 v3, v44
	v_pk_mul_f32 v[0:1], v[0:1], v[2:3]
	v_mov_b32_e32 v54, v45
	v_add_f32_e32 v16, v0, v1
	v_pk_mul_f32 v[0:1], v[70:71], v[32:33] op_sel_hi:[0,1]
	v_pk_mul_f32 v[0:1], v[0:1], v[30:31]
	v_mov_b32_e32 v44, v55
	v_pk_mul_f32 v[2:3], v[0:1], v[54:55]
	v_pk_mul_f32 v[0:1], v[0:1], v[44:45]
	v_sub_f32_e32 v2, v3, v2
	v_add_f32_e32 v0, v0, v1
	v_cvt_pk_bf16_f32 v154, v46, v8
	v_cvt_pk_bf16_f32 v155, v13, v5
	v_cvt_pk_bf16_f32 v156, v7, v10
	v_cvt_pk_bf16_f32 v157, v15, v2
	v_cvt_pk_bf16_f32 v158, v12, v9
	v_cvt_pk_bf16_f32 v159, v4, v6
	v_cvt_pk_bf16_f32 v160, v14, v11
	v_cvt_pk_bf16_f32 v161, v16, v0
	s_barrier
	ds_read_b128 v[0:3], v192
	ds_read_b128 v[52:55], v195 offset:32
	s_waitcnt lgkmcnt(1)
	v_mfma_f32_32x32x16_bf16 v[64:79], v[0:3], v[48:51], 0
	ds_read_b128 v[0:3], v192 offset:32
	ds_read_b128 v[162:165], v196 offset:32
	s_waitcnt lgkmcnt(1)
	v_mfma_f32_32x32x16_bf16 v[64:79], v[0:3], v[154:157], v[64:79]
	ds_read_b128 v[0:3], v192 offset:64
	s_waitcnt lgkmcnt(0)
	v_mfma_f32_32x32x16_bf16 v[64:79], v[0:3], v[116:119], v[64:79]
	ds_read_b128 v[0:3], v192 offset:96
	s_waitcnt lgkmcnt(0)
	v_mfma_f32_32x32x16_bf16 v[64:79], v[0:3], v[158:161], v[64:79]
	ds_read_b128 v[0:3], v193
	s_waitcnt lgkmcnt(0)
	v_mfma_f32_32x32x16_bf16 v[32:47], v[0:3], v[48:51], 0
	ds_read_b128 v[0:3], v193 offset:32
	s_waitcnt lgkmcnt(0)
	v_mfma_f32_32x32x16_bf16 v[32:47], v[0:3], v[154:157], v[32:47]
	ds_read_b128 v[0:3], v193 offset:64
	s_waitcnt lgkmcnt(0)
	v_mfma_f32_32x32x16_bf16 v[32:47], v[0:3], v[116:119], v[32:47]
	ds_read_b128 v[0:3], v193 offset:96
	s_waitcnt lgkmcnt(0)
	v_mfma_f32_32x32x16_bf16 v[32:47], v[0:3], v[158:161], v[32:47]
	ds_read_b128 v[0:3], v194
	s_waitcnt lgkmcnt(0)
	v_mfma_f32_32x32x16_bf16 v[16:31], v[0:3], v[48:51], 0
	ds_read_b128 v[0:3], v194 offset:32
	s_waitcnt lgkmcnt(0)
	v_mfma_f32_32x32x16_bf16 v[16:31], v[0:3], v[154:157], v[16:31]
	ds_read_b128 v[0:3], v194 offset:64
	s_waitcnt lgkmcnt(0)
	v_mfma_f32_32x32x16_bf16 v[16:31], v[0:3], v[116:119], v[16:31]
	ds_read_b128 v[0:3], v194 offset:96
	s_waitcnt lgkmcnt(0)
	v_mfma_f32_32x32x16_bf16 v[16:31], v[0:3], v[158:161], v[16:31]
	ds_read_b128 v[0:3], v195
	s_waitcnt lgkmcnt(0)
	v_mfma_f32_32x32x16_bf16 v[0:15], v[0:3], v[48:51], 0
	v_mfma_f32_32x32x16_bf16 v[0:15], v[52:55], v[154:157], v[0:15]
	ds_read_b128 v[52:55], v195 offset:64
	s_waitcnt lgkmcnt(0)
	v_mfma_f32_32x32x16_bf16 v[0:15], v[52:55], v[116:119], v[0:15]
	ds_read_b128 v[52:55], v195 offset:96
	s_waitcnt lgkmcnt(0)
	v_mfma_f32_32x32x16_bf16 v[0:15], v[52:55], v[158:161], v[0:15]
	ds_read_b128 v[52:55], v196
	s_waitcnt lgkmcnt(0)
	v_mfma_f32_32x32x16_bf16 v[48:63], v[52:55], v[48:51], 0
	v_mfma_f32_32x32x16_bf16 v[48:63], v[162:165], v[154:157], v[48:63]
	ds_read_b128 v[154:157], v196 offset:64
	s_waitcnt lgkmcnt(0)
	v_mfma_f32_32x32x16_bf16 v[48:63], v[154:157], v[116:119], v[48:63]
	ds_read_b128 v[116:119], v196 offset:96
	s_waitcnt lgkmcnt(0)
	v_mfma_f32_32x32x16_bf16 v[48:63], v[116:119], v[158:161], v[48:63]
	s_cbranch_scc0 .LBB0_356
	v_cndmask_b32_e64 v158, v212, v64, s[2:3]
	v_cndmask_b32_e64 v157, v65, v212, s[4:5]
	v_cndmask_b32_e64 v156, v212, v66, s[6:7]
	v_cndmask_b32_e64 v155, v212, v67, s[8:9]
	v_cndmask_b32_e64 v154, v212, v68, s[10:11]
	v_cndmask_b32_e64 v119, v212, v69, s[12:13]
	v_cndmask_b32_e64 v118, v212, v70, s[14:15]
	v_cndmask_b32_e64 v99, v212, v71, s[16:17]
	v_cndmask_b32_e64 v71, v212, v72, s[18:19]
	v_cndmask_b32_e64 v70, v212, v73, s[20:21]
	v_cndmask_b32_e64 v69, v212, v74, s[22:23]
	v_cndmask_b32_e64 v68, v212, v75, s[24:25]
	v_cndmask_b32_e64 v67, v212, v76, s[26:27]
	v_cndmask_b32_e64 v66, v212, v77, s[28:29]
	v_cndmask_b32_e64 v65, v212, v78, s[30:31]
	v_cndmask_b32_e64 v64, v212, v79, s[34:35]
	s_branch .LBB0_357
